# v25 + sample-row reduce phases 7/11/16: late load rounds issued with the first batch
# speedup vs baseline: 1.0002x; 1.0002x over previous
; #define GASP __attribute__((address_space(1)))
; template <int MODE> ...
;     const int lane = threadIdx.x & 63, gw = blockIdx.x * 8 + (threadIdx.x >> 6);
;     if (gw >= NS) return;
;     const int row = NP + gw;
;     f32x4 acc[4];
; #pragma unroll
;     for (int j = 0; j < 4; ++j) acc[j] = (f32x4){0.f, 0.f, 0.f, 0.f};
;     for (int ks = 0; ks < S; ++ks) { const GASP f32x4* sp = (const GASP f32x4*)(slab + ((size_t)ks * NS + gw) * D) + lane;
; #pragma unroll
;         for (int j = 0; j < 4; ++j) acc[j] = acc[j] + sp[64 * j]; }
;     float mu = 0.f, rstd = 1.f;
;     if (STp) { const GASP f32x4* sp = (const GASP f32x4*)(STp + (size_t)row * 32); float s = 0.f, q = 0.f;
; #pragma unroll
;         for (int i = 0; i < 8; ++i) { const f32x4 v = sp[i]; s += v[0] + v[2]; q += v[1] + v[3]; }
;         mu = s * (1.f / D); rstd = 1.f / sqrtf(q * (1.f / D) - mu * mu + LN_EPS); }
;     if (MODE == 0) {
.LBB0_1128:
	s_cmp_lt_i32 s54, 8
	s_cselect_b64 s[0:1], -1, 0
	s_cmp_gt_i32 s55, 7
	s_cselect_b64 s[4:5], -1, 0
	s_and_b64 s[0:1], s[0:1], s[4:5]
	s_andn2_b64 vcc, exec, s[0:1]
	s_cbranch_vccnz .LBB0_1178
	v_lshl_add_u32 v0, s2, 3, v209
	s_movk_i32 s0, 0x400
	v_cmp_gt_i32_e32 vcc, s0, v0
	s_and_saveexec_b64 s[12:13], vcc
	s_cbranch_execz .LBB0_1132
	v_ashrrev_i32_e32 v1, 31, v0
	s_waitcnt vmcnt(0)
	v_and_b32_e32 v28, 63, v208
	s_waitcnt lgkmcnt(0)
	v_lshlrev_b64 v[2:3], 12, v[0:1]
	v_lshl_add_u64 v[2:3], s[52:53], 0, v[2:3]
	v_lshlrev_b32_e32 v16, 4, v28
	v_mov_b32_e32 v17, 0
	v_lshl_add_u64 v[24:25], v[2:3], 0, v[16:17]
	v_add_co_u32_e32 v2, vcc, 0x2fb47000, v24
	s_mov_b32 s0, 0x2ff47000
	s_nop 0
	v_addc_co_u32_e32 v3, vcc, 0, v25, vcc
	global_load_dwordx4 v[12:15], v[2:3], off
	v_add_co_u32_e32 v2, vcc, s0, v24
	v_add_u32_e32 v0, 0x8000, v0
	s_nop 0
	v_addc_co_u32_e32 v3, vcc, 0, v25, vcc
	v_ashrrev_i32_e32 v1, 31, v0
	global_load_dwordx4 v[30:33], v[2:3], off
	v_lshlrev_b64 v[2:3], 7, v[0:1]
	v_lshl_add_u64 v[18:19], s[52:53], 0, v[2:3]
	s_mov_b64 s[0:1], 0x2eba1000
	v_lshl_add_u64 v[2:3], v[18:19], 0, s[0:1]
	s_mov_b32 s0, 0x2eba1000
	v_add_co_u32_e32 v4, vcc, s0, v18
	s_mov_b32 s0, 0x30347000
	s_nop 0
	v_addc_co_u32_e32 v5, vcc, 0, v19, vcc
	global_load_dwordx4 v[34:37], v[4:5], off
	global_load_dwordx4 v[38:41], v[2:3], off offset:16
	v_add_co_u32_e32 v4, vcc, s0, v24
	s_mov_b32 s0, 0x30747000
	s_nop 0
	v_addc_co_u32_e32 v5, vcc, 0, v25, vcc
	global_load_dwordx4 v[42:45], v[4:5], off
	global_load_dwordx4 v[46:49], v[2:3], off offset:32
	global_load_dwordx4 v[50:53], v[2:3], off offset:48
	global_load_dwordx4 v[54:57], v[2:3], off offset:64
	global_load_dwordx4 v[58:61], v[2:3], off offset:80
	global_load_dwordx4 v[62:65], v[2:3], off offset:96
	global_load_dwordx4 v[66:69], v[2:3], off offset:112
	v_add_co_u32_e32 v2, vcc, s0, v24
	v_lshlrev_b64 v[0:1], 11, v[0:1]
	s_nop 0
	v_addc_co_u32_e32 v3, vcc, 0, v25, vcc
	global_load_dwordx4 v[70:73], v[2:3], off
	v_lshlrev_b32_e32 v20, 3, v28
	v_mov_b32_e32 v21, v17
	v_lshl_add_u64 v[0:1], s[42:43], 0, v[0:1]
	v_lshl_add_u64 v[22:23], v[0:1], 0, v[20:21]
	global_load_dwordx2 v[108:109], v[22:23], off
	v_readlane_b32 s0, v252, 1
	v_readlane_b32 s1, v252, 2
	s_load_dwordx4 s[8:11], s[0:1], 0x48
	s_mov_b64 s[0:1], 0x2fb47000
	s_mov_b64 s[4:5], 0x2ff47000
	s_mov_b64 s[14:15], 0x30347000
	v_lshl_add_u64 v[26:27], v[24:25], 0, s[0:1]
	v_lshl_add_u64 v[106:107], v[24:25], 0, s[4:5]
	v_lshl_add_u64 v[110:111], v[24:25], 0, s[14:15]
	global_load_dwordx4 v[74:77], v[26:27], off offset:1024
	global_load_dwordx4 v[78:81], v[26:27], off offset:2048
	global_load_dwordx4 v[82:85], v[106:107], off offset:1024
	global_load_dwordx4 v[86:89], v[106:107], off offset:2048
	global_load_dwordx4 v[0:3], v[106:107], off offset:3072
	global_load_dwordx4 v[90:93], v[110:111], off offset:1024
	global_load_dwordx4 v[94:97], v[110:111], off offset:2048
	s_waitcnt lgkmcnt(0)
	global_load_dwordx4 v[98:101], v16, s[8:9]
	global_load_dwordx4 v[102:105], v16, s[10:11]
	global_load_dwordx4 v[4:7], v[110:111], off offset:3072
	global_load_dwordx4 v[8:11], v[26:27], off offset:3072
	s_mov_b32 s0, 0x3a800000
	s_mov_b64 s[6:7], 0x30747000
	v_lshl_add_u64 v[24:25], v[24:25], 0, s[6:7]
	global_load_dwordx4 v[112:115], v[24:25], off offset:3072
	global_load_dwordx4 v[116:119], v[24:25], off offset:1024
	global_load_dwordx4 v[120:123], v[24:25], off offset:2048
	global_load_dwordx2 v[124:125], v[22:23], off offset:512
	global_load_dwordx2 v[126:127], v[22:23], off offset:1024
	global_load_dwordx2 v[128:129], v[22:23], off offset:1536
	global_load_dwordx4 v[130:133], v16, s[8:9] offset:1024
	global_load_dwordx4 v[134:137], v16, s[10:11] offset:1024
	global_load_dwordx4 v[138:141], v16, s[8:9] offset:2048
	global_load_dwordx4 v[142:145], v16, s[10:11] offset:2048
	global_load_dwordx4 v[146:149], v16, s[8:9] offset:3072
	global_load_dwordx4 v[150:153], v16, s[10:11] offset:3072
	s_waitcnt vmcnt(35)
	v_pk_add_f32 v[14:15], v[14:15], 0 op_sel_hi:[1,0]
	v_pk_add_f32 v[12:13], v[12:13], 0 op_sel_hi:[1,0]
	s_waitcnt vmcnt(34)
	v_pk_add_f32 v[14:15], v[14:15], v[32:33]
	v_pk_add_f32 v[12:13], v[12:13], v[30:31]
	s_waitcnt vmcnt(33)
	v_pk_add_f32 v[26:27], v[34:35], v[36:37]
	s_waitcnt vmcnt(32)
	v_pk_add_f32 v[34:35], v[38:39], v[40:41]
	v_pk_add_f32 v[26:27], v[26:27], 0 op_sel_hi:[1,0]
	s_waitcnt vmcnt(31)
	v_pk_add_f32 v[30:31], v[14:15], v[44:45]
	v_pk_add_f32 v[32:33], v[12:13], v[42:43]
	v_pk_add_f32 v[12:13], v[26:27], v[34:35]
	s_waitcnt vmcnt(30)
	v_pk_add_f32 v[14:15], v[46:47], v[48:49]
	s_waitcnt vmcnt(24)
	v_pk_add_f32 v[38:39], v[30:31], v[72:73]
	v_pk_add_f32 v[12:13], v[12:13], v[14:15]
	v_pk_add_f32 v[14:15], v[50:51], v[52:53]
	v_pk_add_f32 v[40:41], v[32:33], v[70:71]
	v_pk_add_f32 v[12:13], v[12:13], v[14:15]
	v_pk_add_f32 v[14:15], v[54:55], v[56:57]
	s_waitcnt vmcnt(23)
	v_and_b32_e32 v44, 0xffff0000, v109
	v_pk_add_f32 v[12:13], v[12:13], v[14:15]
	v_pk_add_f32 v[14:15], v[58:59], v[60:61]
	s_waitcnt vmcnt(22)
	v_pk_add_f32 v[56:57], v[76:77], 0 op_sel_hi:[1,0]
	v_pk_add_f32 v[12:13], v[12:13], v[14:15]
	v_pk_add_f32 v[14:15], v[62:63], v[64:65]
	v_pk_add_f32 v[58:59], v[74:75], 0 op_sel_hi:[1,0]
	v_pk_add_f32 v[12:13], v[12:13], v[14:15]
	v_pk_add_f32 v[14:15], v[66:67], v[68:69]
	s_waitcnt vmcnt(0)
; #define GASP __attribute__((address_space(1)))
; template <int MODE> ...
;     ...
;         const GASP f32x4* rp = (const GASP f32x4*)(res + (size_t)row * D) + lane;
;         float s = 0.f, q = 0.f;
; #pragma unroll
;         for (int j = 0; j < 4; ++j) { f32x4 r;
;             if (resb) { const u32x2 w = ((const GASP u32x2*)(resb + (size_t)row * D))[64 * j + lane];
;                 r = (f32x4){__uint_as_float(w.x << 16), __uint_as_float(w.x & 0xffff0000u), __uint_as_float(w.y << 16), __uint_as_float(w.y & 0xffff0000u)}; }
;             else r = rp[64 * j];
;             if (STp) r = (r - mu) * rstd * ((const GASP f32x4*)gam)[64 * j + lane] + ((const GASP f32x4*)bet)[64 * j + lane];
;             const f32x4 o = r * ALPHA + acc[j] * scale;
;             if (out) ((GASP f32x4*)(out + (size_t)row * D))[64 * j + lane] = o;
;             if (ob) { u32x2 w; w.x = pk2(o[0], o[1]); w.y = pk2(o[2], o[3]); ((GASP u32x2*)(ob + (size_t)row * D))[64 * j + lane] = w; }
;             s += (o[0] + o[1]) + (o[2] + o[3]); q += (o[0] * o[0] + o[1] * o[1]) + (o[2] * o[2] + o[3] * o[3]); }
	v_pk_add_f32 v[10:11], v[10:11], 0 op_sel_hi:[1,0]
	v_pk_add_f32 v[12:13], v[12:13], v[14:15]
	v_pk_add_f32 v[8:9], v[8:9], 0 op_sel_hi:[1,0]
	v_pk_mul_f32 v[26:27], v[12:13], s[0:1] op_sel_hi:[1,0]
	s_mov_b32 s0, 0xf800000
	v_fma_f32 v12, -v26, v26, v27
	v_add_f32_e32 v12, 0x3727c5ac, v12
	v_mul_f32_e32 v13, 0x4f800000, v12
	v_cmp_gt_f32_e32 vcc, s0, v12
	v_sub_f32_e32 v45, v44, v26
	v_pk_add_f32 v[2:3], v[10:11], v[2:3]
	v_cndmask_b32_e32 v27, v12, v13, vcc
	v_sqrt_f32_e32 v29, v27
	v_pk_add_f32 v[0:1], v[8:9], v[0:1]
	v_pk_add_f32 v[2:3], v[2:3], v[6:7]
	v_add_u32_e32 v30, -1, v29
	v_fma_f32 v31, -v30, v29, v27
	v_cmp_ge_f32_e64 s[6:7], 0, v31
	v_add_u32_e32 v31, 1, v29
	v_pk_add_f32 v[0:1], v[0:1], v[4:5]
	v_cndmask_b32_e64 v30, v29, v30, s[6:7]
	v_fma_f32 v29, -v31, v29, v27
	v_cmp_lt_f32_e64 s[6:7], 0, v29
	v_pk_add_f32 v[2:3], v[2:3], v[114:115]
	v_cndmask_b32_e64 v29, v30, v31, s[6:7]
	v_mul_f32_e32 v30, 0x37800000, v29
	v_cndmask_b32_e32 v29, v29, v30, vcc
	v_mov_b32_e32 v30, 0x260
	v_cmp_class_f32_e32 vcc, v27, v30
	v_cndmask_b32_e32 v27, v29, v27, vcc
	v_div_scale_f32 v29, s[0:1], v27, v27, 1.0
	v_rcp_f32_e32 v42, v29
	s_mov_b32 s6, 0x3f9837f0
	v_pk_add_f32 v[0:1], v[0:1], v[112:113]
	v_fma_f32 v24, -v29, v42, 1.0
	v_fmac_f32_e32 v42, v24, v42
	v_div_scale_f32 v24, vcc, 1.0, v27, 1.0
	v_mul_f32_e32 v25, v24, v42
	v_fma_f32 v43, -v29, v25, v24
	v_fmac_f32_e32 v25, v43, v42
	v_fma_f32 v24, -v29, v25, v24
	v_div_fmas_f32 v24, v24, v42, v25
	v_div_fixup_f32 v24, v24, v27, 1.0
	v_lshlrev_b32_e32 v25, 16, v108
	v_and_b32_e32 v27, 0xffff0000, v108
	v_lshlrev_b32_e32 v29, 16, v109
	v_sub_f32_e32 v43, v27, v26
	v_sub_f32_e32 v42, v25, v26
	v_sub_f32_e32 v44, v29, v26
	v_pk_mul_f32 v[44:45], v[44:45], v[24:25] op_sel_hi:[1,0]
	v_pk_mul_f32 v[42:43], v[42:43], v[24:25] op_sel_hi:[1,0]
	v_pk_fma_f32 v[44:45], v[100:101], v[44:45], v[104:105]
	v_pk_fma_f32 v[42:43], v[98:99], v[42:43], v[102:103]
	v_pk_fma_f32 v[52:53], v[44:45], s[6:7], v[38:39] op_sel_hi:[1,0,1]
	v_pk_fma_f32 v[54:55], v[42:43], s[6:7], v[40:41] op_sel_hi:[1,0,1]
	v_cvt_pk_bf16_f32 v39, v52, v53
	v_cvt_pk_bf16_f32 v38, v54, v55
	global_store_dwordx2 v[22:23], v[38:39], off
	s_nop 0
	v_add_f32_e32 v8, v54, v55
	v_add_f32_e32 v10, v52, v53
	v_mul_f32_e32 v13, v54, v54
	v_mul_f32_e32 v15, v55, v55
	v_lshlrev_b32_e32 v25, 16, v124
	v_and_b32_e32 v27, 0xffff0000, v124
	v_lshlrev_b32_e32 v29, 16, v125
	v_and_b32_e32 v60, 0xffff0000, v125
	v_pk_add_f32 v[46:47], v[56:57], v[84:85]
	v_pk_add_f32 v[56:57], v[58:59], v[82:83]
	v_pk_add_f32 v[46:47], v[46:47], v[92:93]
	v_pk_add_f32 v[56:57], v[56:57], v[90:91]
	v_pk_add_f32 v[32:33], v[46:47], v[118:119]
	v_pk_add_f32 v[30:31], v[56:57], v[116:117]
	v_sub_f32_e32 v47, v27, v26
	v_sub_f32_e32 v46, v25, v26
	v_sub_f32_e32 v57, v60, v26
	v_sub_f32_e32 v56, v29, v26
	v_pk_mul_f32 v[56:57], v[24:25], v[56:57] op_sel_hi:[0,1]
	v_pk_mul_f32 v[46:47], v[24:25], v[46:47] op_sel_hi:[0,1]
	v_lshlrev_b32_e32 v25, 16, v126
	v_and_b32_e32 v27, 0xffff0000, v126
	v_lshlrev_b32_e32 v29, 16, v127
	v_and_b32_e32 v58, 0xffff0000, v127
	v_pk_fma_f32 v[38:39], v[130:131], v[46:47], v[134:135]
	v_pk_fma_f32 v[40:41], v[132:133], v[56:57], v[136:137]
	v_pk_fma_f32 v[44:45], v[38:39], s[6:7], v[30:31] op_sel_hi:[1,0,1]
	v_pk_fma_f32 v[42:43], v[40:41], s[6:7], v[32:33] op_sel_hi:[1,0,1]
	v_cvt_pk_bf16_f32 v30, v44, v45
	v_cvt_pk_bf16_f32 v31, v42, v43
	global_store_dwordx2 v[22:23], v[30:31], off offset:512
	s_nop 0
	v_pk_add_f32 v[46:47], v[80:81], 0 op_sel_hi:[1,0]
	v_pk_add_f32 v[56:57], v[78:79], 0 op_sel_hi:[1,0]
	v_pk_add_f32 v[46:47], v[46:47], v[88:89]
	v_pk_add_f32 v[48:49], v[56:57], v[86:87]
	v_pk_add_f32 v[46:47], v[46:47], v[96:97]
	v_pk_add_f32 v[48:49], v[48:49], v[94:95]
	v_pk_add_f32 v[36:37], v[46:47], v[122:123]
	v_pk_add_f32 v[34:35], v[48:49], v[120:121]
	v_sub_f32_e32 v47, v27, v26
	v_sub_f32_e32 v46, v25, v26
	v_sub_f32_e32 v49, v58, v26
	v_sub_f32_e32 v48, v29, v26
	v_pk_mul_f32 v[48:49], v[24:25], v[48:49] op_sel_hi:[0,1]
	v_pk_mul_f32 v[46:47], v[24:25], v[46:47] op_sel_hi:[0,1]
	v_lshlrev_b32_e32 v27, 16, v129
	v_sub_f32_e32 v6, v27, v26
	v_mul_f32_e32 v27, v53, v53
	v_mul_f32_e32 v9, v44, v44
	v_mul_f32_e32 v11, v45, v45
	v_mov_b32_e32 v12, v44
	v_mov_b32_e32 v14, v45
	v_pk_add_f32 v[12:13], v[12:13], v[14:15]
	v_pk_add_f32 v[8:9], v[8:9], v[10:11]
	v_pk_fma_f32 v[30:31], v[138:139], v[46:47], v[142:143]
	v_pk_fma_f32 v[32:33], v[140:141], v[48:49], v[144:145]
	v_pk_fma_f32 v[40:41], v[30:31], s[6:7], v[34:35] op_sel_hi:[1,0,1]
	v_pk_fma_f32 v[38:39], v[32:33], s[6:7], v[36:37] op_sel_hi:[1,0,1]
	v_cvt_pk_bf16_f32 v30, v40, v41
	v_cvt_pk_bf16_f32 v31, v38, v39
	global_store_dwordx2 v[22:23], v[30:31], off offset:1024
	s_nop 0
	v_mbcnt_lo_u32_b32 v16, -1, 0
	v_mbcnt_hi_u32_b32 v29, -1, v16
	v_and_b32_e32 v16, 64, v29
	v_xor_b32_e32 v25, 1, v29
	v_add_u32_e32 v46, 64, v16
	v_cmp_lt_i32_e32 vcc, v25, v46
	v_and_b32_e32 v48, 0xffff0000, v129
	v_sub_f32_e32 v7, v48, v26
	v_cndmask_b32_e32 v16, v29, v25, vcc
	v_lshlrev_b32_e32 v47, 2, v16
	v_lshlrev_b32_e32 v16, 16, v128
	v_and_b32_e32 v25, 0xffff0000, v128
	v_sub_f32_e32 v5, v25, v26
	v_sub_f32_e32 v4, v16, v26
	v_mul_f32_e32 v16, v42, v42
	v_pk_mul_f32 v[6:7], v[24:25], v[6:7] op_sel_hi:[0,1]
	v_pk_mul_f32 v[4:5], v[24:25], v[4:5] op_sel_hi:[0,1]
	v_mul_f32_e32 v25, v52, v52
	v_mov_b32_e32 v24, v42
	v_mov_b32_e32 v26, v43
	v_pk_fma_f32 v[42:43], v[42:43], v[42:43], v[16:17] op_sel_hi:[1,1,0]
	v_pk_add_f32 v[14:15], v[24:25], v[26:27]
	v_mov_b32_e32 v42, v17
	v_pk_add_f32 v[10:11], v[12:13], v[14:15]
	v_pk_add_f32 v[8:9], v[8:9], v[42:43]
	v_mul_f32_e32 v13, v41, v41
	v_pk_add_f32 v[8:9], v[10:11], v[8:9]
	v_mul_f32_e32 v11, v40, v40
	v_mul_f32_e32 v15, v38, v38
	v_mul_f32_e32 v17, v39, v39
	v_mov_b32_e32 v10, v40
	v_mov_b32_e32 v12, v41
	v_mov_b32_e32 v14, v38
	v_mov_b32_e32 v16, v39
	v_pk_add_f32 v[10:11], v[10:11], v[12:13]
	v_pk_add_f32 v[12:13], v[14:15], v[16:17]
	v_pk_fma_f32 v[4:5], v[146:147], v[4:5], v[150:151]
	v_pk_fma_f32 v[6:7], v[148:149], v[6:7], v[152:153]
	v_pk_add_f32 v[10:11], v[10:11], v[12:13]
	v_pk_fma_f32 v[6:7], v[6:7], s[6:7], v[2:3] op_sel_hi:[1,0,1]
	v_pk_fma_f32 v[4:5], v[4:5], s[6:7], v[0:1] op_sel_hi:[1,0,1]
	v_pk_add_f32 v[8:9], v[8:9], v[10:11]
	v_mul_f32_e32 v1, v4, v4
	v_mul_f32_e32 v3, v5, v5
	v_mul_f32_e32 v11, v6, v6
	v_mul_f32_e32 v13, v7, v7
	v_mov_b32_e32 v0, v4
	v_mov_b32_e32 v2, v5
	v_mov_b32_e32 v10, v6
	v_mov_b32_e32 v12, v7
	v_pk_add_f32 v[0:1], v[0:1], v[2:3]
	v_pk_add_f32 v[2:3], v[10:11], v[12:13]
	v_cvt_pk_bf16_f32 v4, v4, v5
	v_pk_add_f32 v[0:1], v[0:1], v[2:3]
	v_cvt_pk_bf16_f32 v5, v6, v7
	v_pk_add_f32 v[0:1], v[8:9], v[0:1]
	ds_bpermute_b32 v2, v47, v0
	ds_bpermute_b32 v3, v47, v1
	v_xor_b32_e32 v8, 2, v29
	v_cmp_lt_i32_e32 vcc, v8, v46
	global_store_dwordx2 v[22:23], v[4:5], off offset:1536
	s_waitcnt lgkmcnt(0)
; #define GASP __attribute__((address_space(1)))
; template <int MODE> ...
;     ...
;         if (STn) { s = wave_sum(s); q = wave_sum(q);
;             if (lane < 16) *(GASP f32x2*)(STn + (size_t)row * 32 + 2 * lane) = lane == 0 ? (f32x2){s, q} : (f32x2){0.f, 0.f}; }
	v_pk_add_f32 v[0:1], v[0:1], v[2:3]
	v_cndmask_b32_e32 v8, v29, v8, vcc
	v_lshlrev_b32_e32 v8, 2, v8
	ds_bpermute_b32 v2, v8, v0
	ds_bpermute_b32 v3, v8, v1
	v_xor_b32_e32 v8, 4, v29
	v_cmp_lt_i32_e32 vcc, v8, v46
	s_waitcnt lgkmcnt(0)
	v_pk_add_f32 v[0:1], v[0:1], v[2:3]
	v_cndmask_b32_e32 v8, v29, v8, vcc
	v_lshlrev_b32_e32 v8, 2, v8
	ds_bpermute_b32 v2, v8, v0
	ds_bpermute_b32 v3, v8, v1
	v_xor_b32_e32 v8, 8, v29
	v_cmp_lt_i32_e32 vcc, v8, v46
	s_waitcnt lgkmcnt(0)
	v_pk_add_f32 v[0:1], v[0:1], v[2:3]
	v_cndmask_b32_e32 v8, v29, v8, vcc
	v_lshlrev_b32_e32 v8, 2, v8
	ds_bpermute_b32 v2, v8, v0
	ds_bpermute_b32 v3, v8, v1
	v_xor_b32_e32 v8, 16, v29
	v_cmp_lt_i32_e32 vcc, v8, v46
	s_waitcnt lgkmcnt(0)
	v_pk_add_f32 v[0:1], v[0:1], v[2:3]
	v_cndmask_b32_e32 v8, v29, v8, vcc
	v_lshlrev_b32_e32 v8, 2, v8
	ds_bpermute_b32 v2, v8, v0
	ds_bpermute_b32 v3, v8, v1
	v_xor_b32_e32 v8, 32, v29
	v_cmp_lt_i32_e32 vcc, v8, v46
	s_waitcnt lgkmcnt(0)
	v_pk_add_f32 v[0:1], v[0:1], v[2:3]
	v_cndmask_b32_e32 v8, v29, v8, vcc
	v_lshlrev_b32_e32 v8, 2, v8
	ds_bpermute_b32 v2, v8, v0
	ds_bpermute_b32 v3, v8, v1
	v_cmp_gt_u32_e32 vcc, 16, v28
	s_and_b64 exec, exec, vcc
	s_cbranch_execz .LBB0_1132
	v_lshl_add_u64 v[4:5], v[18:19], 0, v[20:21]
	s_waitcnt lgkmcnt(0)
	v_pk_add_f32 v[0:1], v[0:1], v[2:3]
	v_cmp_eq_u32_e32 vcc, 0, v28
	s_nop 1
	v_cndmask_b32_e32 v1, 0, v1, vcc
	v_cndmask_b32_e32 v0, 0, v0, vcc
	v_add_co_u32_e32 v2, vcc, 0x2efc1000, v4
	s_nop 1
	v_addc_co_u32_e32 v3, vcc, 0, v5, vcc
	global_store_dwordx2 v[2:3], v[0:1], off

; #define GASP __attribute__((address_space(1)))
; template <int MODE> ...
;     const int lane = threadIdx.x & 63, gw = blockIdx.x * 8 + (threadIdx.x >> 6);
;     if (gw >= NS) return;
;     const int row = NP + gw;
;     f32x4 acc[4];
; #pragma unroll
;     for (int j = 0; j < 4; ++j) acc[j] = (f32x4){0.f, 0.f, 0.f, 0.f};
;     for (int ks = 0; ks < S; ++ks) { const GASP f32x4* sp = (const GASP f32x4*)(slab + ((size_t)ks * NS + gw) * D) + lane;
; #pragma unroll
;         for (int j = 0; j < 4; ++j) acc[j] = acc[j] + sp[64 * j]; }
;     float mu = 0.f, rstd = 1.f;
;     if (STp) { const GASP f32x4* sp = (const GASP f32x4*)(STp + (size_t)row * 32); float s = 0.f, q = 0.f;
; #pragma unroll
;         for (int i = 0; i < 8; ++i) { const f32x4 v = sp[i]; s += v[0] + v[2]; q += v[1] + v[3]; }
;         mu = s * (1.f / D); rstd = 1.f / sqrtf(q * (1.f / D) - mu * mu + LN_EPS); }
;     if (MODE == 0) {
.LBB0_1508:
	s_cmp_lt_i32 s54, 12
	s_cselect_b64 s[0:1], -1, 0
	s_cmp_gt_i32 s55, 11
	s_cselect_b64 s[4:5], -1, 0
	s_and_b64 s[0:1], s[0:1], s[4:5]
	s_andn2_b64 vcc, exec, s[0:1]
	s_cbranch_vccnz .LBB0_1558
	s_waitcnt lgkmcnt(0)
	v_lshl_add_u32 v0, s2, 3, v209
	s_movk_i32 s0, 0x400
	v_cmp_gt_i32_e32 vcc, s0, v0
	s_and_saveexec_b64 s[12:13], vcc
	s_cbranch_execz .LBB0_1512
	v_ashrrev_i32_e32 v1, 31, v0
	s_waitcnt vmcnt(0)
	v_and_b32_e32 v28, 63, v208
	v_lshlrev_b64 v[2:3], 12, v[0:1]
	v_lshl_add_u64 v[2:3], s[52:53], 0, v[2:3]
	v_lshlrev_b32_e32 v16, 4, v28
	v_mov_b32_e32 v17, 0
	v_lshl_add_u64 v[24:25], v[2:3], 0, v[16:17]
	v_add_co_u32_e32 v2, vcc, 0x2fb47000, v24
	s_mov_b32 s0, 0x2ff47000
	s_nop 0
	v_addc_co_u32_e32 v3, vcc, 0, v25, vcc
	global_load_dwordx4 v[12:15], v[2:3], off
	v_add_co_u32_e32 v2, vcc, s0, v24
	v_add_u32_e32 v0, 0x8000, v0
	s_nop 0
	v_addc_co_u32_e32 v3, vcc, 0, v25, vcc
	v_ashrrev_i32_e32 v1, 31, v0
	global_load_dwordx4 v[30:33], v[2:3], off
	v_lshlrev_b64 v[2:3], 7, v[0:1]
	v_lshl_add_u64 v[18:19], s[52:53], 0, v[2:3]
	s_mov_b64 s[0:1], 0x2efc1000
	v_lshl_add_u64 v[2:3], v[18:19], 0, s[0:1]
	s_mov_b32 s0, 0x2efc1000
	v_add_co_u32_e32 v4, vcc, s0, v18
	s_mov_b32 s0, 0x30347000
	s_nop 0
	v_addc_co_u32_e32 v5, vcc, 0, v19, vcc
	global_load_dwordx4 v[34:37], v[4:5], off
	global_load_dwordx4 v[38:41], v[2:3], off offset:16
	v_add_co_u32_e32 v4, vcc, s0, v24
	s_mov_b32 s0, 0x30747000
	s_nop 0
	v_addc_co_u32_e32 v5, vcc, 0, v25, vcc
	global_load_dwordx4 v[42:45], v[4:5], off
	global_load_dwordx4 v[46:49], v[2:3], off offset:32
	global_load_dwordx4 v[50:53], v[2:3], off offset:48
	global_load_dwordx4 v[54:57], v[2:3], off offset:64
	global_load_dwordx4 v[58:61], v[2:3], off offset:80
	global_load_dwordx4 v[62:65], v[2:3], off offset:96
	global_load_dwordx4 v[66:69], v[2:3], off offset:112
	v_add_co_u32_e32 v2, vcc, s0, v24
	v_lshlrev_b64 v[0:1], 11, v[0:1]
	s_nop 0
	v_addc_co_u32_e32 v3, vcc, 0, v25, vcc
	global_load_dwordx4 v[70:73], v[2:3], off
	v_lshlrev_b32_e32 v20, 3, v28
	v_mov_b32_e32 v21, v17
	v_lshl_add_u64 v[0:1], s[42:43], 0, v[0:1]
	v_lshl_add_u64 v[22:23], v[0:1], 0, v[20:21]
	global_load_dwordx2 v[108:109], v[22:23], off
	v_readlane_b32 s0, v252, 1
	v_readlane_b32 s1, v252, 2
	s_load_dwordx4 s[8:11], s[0:1], 0xb0
	s_mov_b64 s[0:1], 0x2fb47000
	s_mov_b64 s[4:5], 0x2ff47000
	s_mov_b64 s[14:15], 0x30347000
	v_lshl_add_u64 v[26:27], v[24:25], 0, s[0:1]
	v_lshl_add_u64 v[106:107], v[24:25], 0, s[4:5]
	v_lshl_add_u64 v[110:111], v[24:25], 0, s[14:15]
	global_load_dwordx4 v[74:77], v[26:27], off offset:1024
	global_load_dwordx4 v[78:81], v[26:27], off offset:2048
	global_load_dwordx4 v[82:85], v[106:107], off offset:1024
	global_load_dwordx4 v[86:89], v[106:107], off offset:2048
	global_load_dwordx4 v[0:3], v[106:107], off offset:3072
	global_load_dwordx4 v[90:93], v[110:111], off offset:1024
	global_load_dwordx4 v[94:97], v[110:111], off offset:2048
	s_waitcnt lgkmcnt(0)
	global_load_dwordx4 v[98:101], v16, s[8:9]
	global_load_dwordx4 v[102:105], v16, s[10:11]
	global_load_dwordx4 v[4:7], v[110:111], off offset:3072
	global_load_dwordx4 v[8:11], v[26:27], off offset:3072
	s_mov_b32 s0, 0x3a800000
	s_mov_b64 s[6:7], 0x30747000
	v_lshl_add_u64 v[24:25], v[24:25], 0, s[6:7]
	global_load_dwordx4 v[112:115], v[24:25], off offset:3072
	global_load_dwordx4 v[116:119], v[24:25], off offset:1024
	global_load_dwordx4 v[120:123], v[24:25], off offset:2048
	global_load_dwordx2 v[124:125], v[22:23], off offset:512
	global_load_dwordx2 v[126:127], v[22:23], off offset:1024
	global_load_dwordx2 v[128:129], v[22:23], off offset:1536
	global_load_dwordx4 v[130:133], v16, s[8:9] offset:1024
	global_load_dwordx4 v[134:137], v16, s[10:11] offset:1024
	global_load_dwordx4 v[138:141], v16, s[8:9] offset:2048
	global_load_dwordx4 v[142:145], v16, s[10:11] offset:2048
	global_load_dwordx4 v[146:149], v16, s[8:9] offset:3072
	global_load_dwordx4 v[150:153], v16, s[10:11] offset:3072
	s_waitcnt vmcnt(35)
	v_pk_add_f32 v[14:15], v[14:15], 0 op_sel_hi:[1,0]
	v_pk_add_f32 v[12:13], v[12:13], 0 op_sel_hi:[1,0]
	s_waitcnt vmcnt(34)
	v_pk_add_f32 v[14:15], v[14:15], v[32:33]
	v_pk_add_f32 v[12:13], v[12:13], v[30:31]
	s_waitcnt vmcnt(33)
	v_pk_add_f32 v[26:27], v[34:35], v[36:37]
	s_waitcnt vmcnt(32)
	v_pk_add_f32 v[34:35], v[38:39], v[40:41]
	v_pk_add_f32 v[26:27], v[26:27], 0 op_sel_hi:[1,0]
	s_waitcnt vmcnt(31)
	v_pk_add_f32 v[30:31], v[14:15], v[44:45]
	v_pk_add_f32 v[32:33], v[12:13], v[42:43]
	v_pk_add_f32 v[12:13], v[26:27], v[34:35]
	s_waitcnt vmcnt(30)
	v_pk_add_f32 v[14:15], v[46:47], v[48:49]
	s_waitcnt vmcnt(24)
	v_pk_add_f32 v[38:39], v[30:31], v[72:73]
	v_pk_add_f32 v[12:13], v[12:13], v[14:15]
	v_pk_add_f32 v[14:15], v[50:51], v[52:53]
	v_pk_add_f32 v[40:41], v[32:33], v[70:71]
	v_pk_add_f32 v[12:13], v[12:13], v[14:15]
	v_pk_add_f32 v[14:15], v[54:55], v[56:57]
	s_waitcnt vmcnt(23)
	v_and_b32_e32 v44, 0xffff0000, v109
	v_pk_add_f32 v[12:13], v[12:13], v[14:15]
	v_pk_add_f32 v[14:15], v[58:59], v[60:61]
	s_waitcnt vmcnt(22)
	v_pk_add_f32 v[56:57], v[76:77], 0 op_sel_hi:[1,0]
	v_pk_add_f32 v[12:13], v[12:13], v[14:15]
	v_pk_add_f32 v[14:15], v[62:63], v[64:65]
	v_pk_add_f32 v[58:59], v[74:75], 0 op_sel_hi:[1,0]
	v_pk_add_f32 v[12:13], v[12:13], v[14:15]
	v_pk_add_f32 v[14:15], v[66:67], v[68:69]
	s_waitcnt vmcnt(0)
; #define GASP __attribute__((address_space(1)))
; template <int MODE> ...
;     ...
;         const GASP f32x4* rp = (const GASP f32x4*)(res + (size_t)row * D) + lane;
;         float s = 0.f, q = 0.f;
; #pragma unroll
;         for (int j = 0; j < 4; ++j) { f32x4 r;
;             if (resb) { const u32x2 w = ((const GASP u32x2*)(resb + (size_t)row * D))[64 * j + lane];
;                 r = (f32x4){__uint_as_float(w.x << 16), __uint_as_float(w.x & 0xffff0000u), __uint_as_float(w.y << 16), __uint_as_float(w.y & 0xffff0000u)}; }
;             else r = rp[64 * j];
;             if (STp) r = (r - mu) * rstd * ((const GASP f32x4*)gam)[64 * j + lane] + ((const GASP f32x4*)bet)[64 * j + lane];
;             const f32x4 o = r * ALPHA + acc[j] * scale;
;             if (out) ((GASP f32x4*)(out + (size_t)row * D))[64 * j + lane] = o;
;             if (ob) { u32x2 w; w.x = pk2(o[0], o[1]); w.y = pk2(o[2], o[3]); ((GASP u32x2*)(ob + (size_t)row * D))[64 * j + lane] = w; }
;             s += (o[0] + o[1]) + (o[2] + o[3]); q += (o[0] * o[0] + o[1] * o[1]) + (o[2] * o[2] + o[3] * o[3]); }
	v_pk_add_f32 v[10:11], v[10:11], 0 op_sel_hi:[1,0]
	v_pk_add_f32 v[12:13], v[12:13], v[14:15]
	v_pk_add_f32 v[8:9], v[8:9], 0 op_sel_hi:[1,0]
	v_pk_mul_f32 v[26:27], v[12:13], s[0:1] op_sel_hi:[1,0]
	s_mov_b32 s0, 0xf800000
	v_fma_f32 v12, -v26, v26, v27
	v_add_f32_e32 v12, 0x3727c5ac, v12
	v_mul_f32_e32 v13, 0x4f800000, v12
	v_cmp_gt_f32_e32 vcc, s0, v12
	v_sub_f32_e32 v45, v44, v26
	v_pk_add_f32 v[2:3], v[10:11], v[2:3]
	v_cndmask_b32_e32 v27, v12, v13, vcc
	v_sqrt_f32_e32 v29, v27
	v_pk_add_f32 v[0:1], v[8:9], v[0:1]
	v_pk_add_f32 v[2:3], v[2:3], v[6:7]
	v_add_u32_e32 v30, -1, v29
	v_fma_f32 v31, -v30, v29, v27
	v_cmp_ge_f32_e64 s[6:7], 0, v31
	v_add_u32_e32 v31, 1, v29
	v_pk_add_f32 v[0:1], v[0:1], v[4:5]
	v_cndmask_b32_e64 v30, v29, v30, s[6:7]
	v_fma_f32 v29, -v31, v29, v27
	v_cmp_lt_f32_e64 s[6:7], 0, v29
	v_pk_add_f32 v[2:3], v[2:3], v[114:115]
	v_cndmask_b32_e64 v29, v30, v31, s[6:7]
	v_mul_f32_e32 v30, 0x37800000, v29
	v_cndmask_b32_e32 v29, v29, v30, vcc
	v_mov_b32_e32 v30, 0x260
	v_cmp_class_f32_e32 vcc, v27, v30
	v_cndmask_b32_e32 v27, v29, v27, vcc
	v_div_scale_f32 v29, s[0:1], v27, v27, 1.0
	v_rcp_f32_e32 v42, v29
	s_mov_b32 s6, 0x3f9837f0
	v_pk_add_f32 v[0:1], v[0:1], v[112:113]
	v_fma_f32 v24, -v29, v42, 1.0
	v_fmac_f32_e32 v42, v24, v42
	v_div_scale_f32 v24, vcc, 1.0, v27, 1.0
	v_mul_f32_e32 v25, v24, v42
	v_fma_f32 v43, -v29, v25, v24
	v_fmac_f32_e32 v25, v43, v42
	v_fma_f32 v24, -v29, v25, v24
	v_div_fmas_f32 v24, v24, v42, v25
	v_div_fixup_f32 v24, v24, v27, 1.0
	v_lshlrev_b32_e32 v25, 16, v108
	v_and_b32_e32 v27, 0xffff0000, v108
	v_lshlrev_b32_e32 v29, 16, v109
	v_sub_f32_e32 v43, v27, v26
	v_sub_f32_e32 v42, v25, v26
	v_sub_f32_e32 v44, v29, v26
	v_pk_mul_f32 v[44:45], v[44:45], v[24:25] op_sel_hi:[1,0]
	v_pk_mul_f32 v[42:43], v[42:43], v[24:25] op_sel_hi:[1,0]
	v_pk_fma_f32 v[44:45], v[100:101], v[44:45], v[104:105]
	v_pk_fma_f32 v[42:43], v[98:99], v[42:43], v[102:103]
	v_pk_fma_f32 v[52:53], v[44:45], s[6:7], v[38:39] op_sel_hi:[1,0,1]
	v_pk_fma_f32 v[54:55], v[42:43], s[6:7], v[40:41] op_sel_hi:[1,0,1]
	v_cvt_pk_bf16_f32 v39, v52, v53
	v_cvt_pk_bf16_f32 v38, v54, v55
	global_store_dwordx2 v[22:23], v[38:39], off
	s_nop 0
	v_add_f32_e32 v8, v54, v55
	v_add_f32_e32 v10, v52, v53
	v_mul_f32_e32 v13, v54, v54
	v_mul_f32_e32 v15, v55, v55
	v_lshlrev_b32_e32 v25, 16, v124
	v_and_b32_e32 v27, 0xffff0000, v124
	v_lshlrev_b32_e32 v29, 16, v125
	v_and_b32_e32 v60, 0xffff0000, v125
	v_pk_add_f32 v[46:47], v[56:57], v[84:85]
	v_pk_add_f32 v[56:57], v[58:59], v[82:83]
	v_pk_add_f32 v[46:47], v[46:47], v[92:93]
	v_pk_add_f32 v[56:57], v[56:57], v[90:91]
	v_pk_add_f32 v[32:33], v[46:47], v[118:119]
	v_pk_add_f32 v[30:31], v[56:57], v[116:117]
	v_sub_f32_e32 v47, v27, v26
	v_sub_f32_e32 v46, v25, v26
	v_sub_f32_e32 v57, v60, v26
	v_sub_f32_e32 v56, v29, v26
	v_pk_mul_f32 v[56:57], v[24:25], v[56:57] op_sel_hi:[0,1]
	v_pk_mul_f32 v[46:47], v[24:25], v[46:47] op_sel_hi:[0,1]
	v_lshlrev_b32_e32 v25, 16, v126
	v_and_b32_e32 v27, 0xffff0000, v126
	v_lshlrev_b32_e32 v29, 16, v127
	v_and_b32_e32 v58, 0xffff0000, v127
	v_pk_fma_f32 v[38:39], v[130:131], v[46:47], v[134:135]
	v_pk_fma_f32 v[40:41], v[132:133], v[56:57], v[136:137]
	v_pk_fma_f32 v[44:45], v[38:39], s[6:7], v[30:31] op_sel_hi:[1,0,1]
	v_pk_fma_f32 v[42:43], v[40:41], s[6:7], v[32:33] op_sel_hi:[1,0,1]
	v_cvt_pk_bf16_f32 v30, v44, v45
	v_cvt_pk_bf16_f32 v31, v42, v43
	global_store_dwordx2 v[22:23], v[30:31], off offset:512
	s_nop 0
	v_pk_add_f32 v[46:47], v[80:81], 0 op_sel_hi:[1,0]
	v_pk_add_f32 v[56:57], v[78:79], 0 op_sel_hi:[1,0]
	v_pk_add_f32 v[46:47], v[46:47], v[88:89]
	v_pk_add_f32 v[48:49], v[56:57], v[86:87]
	v_pk_add_f32 v[46:47], v[46:47], v[96:97]
	v_pk_add_f32 v[48:49], v[48:49], v[94:95]
	v_pk_add_f32 v[36:37], v[46:47], v[122:123]
	v_pk_add_f32 v[34:35], v[48:49], v[120:121]
	v_sub_f32_e32 v47, v27, v26
	v_sub_f32_e32 v46, v25, v26
	v_sub_f32_e32 v49, v58, v26
	v_sub_f32_e32 v48, v29, v26
	v_pk_mul_f32 v[48:49], v[24:25], v[48:49] op_sel_hi:[0,1]
	v_pk_mul_f32 v[46:47], v[24:25], v[46:47] op_sel_hi:[0,1]
	v_lshlrev_b32_e32 v27, 16, v129
	v_sub_f32_e32 v6, v27, v26
	v_mul_f32_e32 v27, v53, v53
	v_mul_f32_e32 v9, v44, v44
	v_mul_f32_e32 v11, v45, v45
	v_mov_b32_e32 v12, v44
	v_mov_b32_e32 v14, v45
	v_pk_add_f32 v[12:13], v[12:13], v[14:15]
	v_pk_add_f32 v[8:9], v[8:9], v[10:11]
	v_pk_fma_f32 v[30:31], v[138:139], v[46:47], v[142:143]
	v_pk_fma_f32 v[32:33], v[140:141], v[48:49], v[144:145]
	v_pk_fma_f32 v[40:41], v[30:31], s[6:7], v[34:35] op_sel_hi:[1,0,1]
	v_pk_fma_f32 v[38:39], v[32:33], s[6:7], v[36:37] op_sel_hi:[1,0,1]
	v_cvt_pk_bf16_f32 v30, v40, v41
	v_cvt_pk_bf16_f32 v31, v38, v39
	global_store_dwordx2 v[22:23], v[30:31], off offset:1024
	s_nop 0
	v_mbcnt_lo_u32_b32 v16, -1, 0
	v_mbcnt_hi_u32_b32 v29, -1, v16
	v_and_b32_e32 v16, 64, v29
	v_xor_b32_e32 v25, 1, v29
	v_add_u32_e32 v46, 64, v16
	v_cmp_lt_i32_e32 vcc, v25, v46
	v_and_b32_e32 v48, 0xffff0000, v129
	v_sub_f32_e32 v7, v48, v26
	v_cndmask_b32_e32 v16, v29, v25, vcc
	v_lshlrev_b32_e32 v47, 2, v16
	v_lshlrev_b32_e32 v16, 16, v128
	v_and_b32_e32 v25, 0xffff0000, v128
	v_sub_f32_e32 v5, v25, v26
	v_sub_f32_e32 v4, v16, v26
	v_mul_f32_e32 v16, v42, v42
	v_pk_mul_f32 v[6:7], v[24:25], v[6:7] op_sel_hi:[0,1]
	v_pk_mul_f32 v[4:5], v[24:25], v[4:5] op_sel_hi:[0,1]
	v_mul_f32_e32 v25, v52, v52
	v_mov_b32_e32 v24, v42
	v_mov_b32_e32 v26, v43
	v_pk_fma_f32 v[42:43], v[42:43], v[42:43], v[16:17] op_sel_hi:[1,1,0]
	v_pk_add_f32 v[14:15], v[24:25], v[26:27]
	v_mov_b32_e32 v42, v17
	v_pk_add_f32 v[10:11], v[12:13], v[14:15]
	v_pk_add_f32 v[8:9], v[8:9], v[42:43]
	v_mul_f32_e32 v13, v41, v41
	v_pk_add_f32 v[8:9], v[10:11], v[8:9]
	v_mul_f32_e32 v11, v40, v40
	v_mul_f32_e32 v15, v38, v38
	v_mul_f32_e32 v17, v39, v39
	v_mov_b32_e32 v10, v40
	v_mov_b32_e32 v12, v41
	v_mov_b32_e32 v14, v38
	v_mov_b32_e32 v16, v39
	v_pk_add_f32 v[10:11], v[10:11], v[12:13]
	v_pk_add_f32 v[12:13], v[14:15], v[16:17]
	v_pk_fma_f32 v[4:5], v[146:147], v[4:5], v[150:151]
	v_pk_fma_f32 v[6:7], v[148:149], v[6:7], v[152:153]
	v_pk_add_f32 v[10:11], v[10:11], v[12:13]
	v_pk_fma_f32 v[6:7], v[6:7], s[6:7], v[2:3] op_sel_hi:[1,0,1]
	v_pk_fma_f32 v[4:5], v[4:5], s[6:7], v[0:1] op_sel_hi:[1,0,1]
	v_pk_add_f32 v[8:9], v[8:9], v[10:11]
	v_mul_f32_e32 v1, v4, v4
	v_mul_f32_e32 v3, v5, v5
	v_mul_f32_e32 v11, v6, v6
	v_mul_f32_e32 v13, v7, v7
	v_mov_b32_e32 v0, v4
	v_mov_b32_e32 v2, v5
	v_mov_b32_e32 v10, v6
	v_mov_b32_e32 v12, v7
	v_pk_add_f32 v[0:1], v[0:1], v[2:3]
	v_pk_add_f32 v[2:3], v[10:11], v[12:13]
	v_cvt_pk_bf16_f32 v4, v4, v5
	v_pk_add_f32 v[0:1], v[0:1], v[2:3]
	v_cvt_pk_bf16_f32 v5, v6, v7
	v_pk_add_f32 v[0:1], v[8:9], v[0:1]
	ds_bpermute_b32 v2, v47, v0
	ds_bpermute_b32 v3, v47, v1
	v_xor_b32_e32 v8, 2, v29
	v_cmp_lt_i32_e32 vcc, v8, v46
	global_store_dwordx2 v[22:23], v[4:5], off offset:1536
	s_waitcnt lgkmcnt(0)
; #define GASP __attribute__((address_space(1)))
; template <int MODE> ...
;     ...
;         if (STn) { s = wave_sum(s); q = wave_sum(q);
;             if (lane < 16) *(GASP f32x2*)(STn + (size_t)row * 32 + 2 * lane) = lane == 0 ? (f32x2){s, q} : (f32x2){0.f, 0.f}; }
	v_pk_add_f32 v[0:1], v[0:1], v[2:3]
	v_cndmask_b32_e32 v8, v29, v8, vcc
	v_lshlrev_b32_e32 v8, 2, v8
	ds_bpermute_b32 v2, v8, v0
	ds_bpermute_b32 v3, v8, v1
	v_xor_b32_e32 v8, 4, v29
	v_cmp_lt_i32_e32 vcc, v8, v46
	s_waitcnt lgkmcnt(0)
	v_pk_add_f32 v[0:1], v[0:1], v[2:3]
	v_cndmask_b32_e32 v8, v29, v8, vcc
	v_lshlrev_b32_e32 v8, 2, v8
	ds_bpermute_b32 v2, v8, v0
	ds_bpermute_b32 v3, v8, v1
	v_xor_b32_e32 v8, 8, v29
	v_cmp_lt_i32_e32 vcc, v8, v46
	s_waitcnt lgkmcnt(0)
	v_pk_add_f32 v[0:1], v[0:1], v[2:3]
	v_cndmask_b32_e32 v8, v29, v8, vcc
	v_lshlrev_b32_e32 v8, 2, v8
	ds_bpermute_b32 v2, v8, v0
	ds_bpermute_b32 v3, v8, v1
	v_xor_b32_e32 v8, 16, v29
	v_cmp_lt_i32_e32 vcc, v8, v46
	s_waitcnt lgkmcnt(0)
	v_pk_add_f32 v[0:1], v[0:1], v[2:3]
	v_cndmask_b32_e32 v8, v29, v8, vcc
	v_lshlrev_b32_e32 v8, 2, v8
	ds_bpermute_b32 v2, v8, v0
	ds_bpermute_b32 v3, v8, v1
	v_xor_b32_e32 v8, 32, v29
	v_cmp_lt_i32_e32 vcc, v8, v46
	s_waitcnt lgkmcnt(0)
	v_pk_add_f32 v[0:1], v[0:1], v[2:3]
	v_cndmask_b32_e32 v8, v29, v8, vcc
	v_lshlrev_b32_e32 v8, 2, v8
	ds_bpermute_b32 v2, v8, v0
	ds_bpermute_b32 v3, v8, v1
	v_cmp_gt_u32_e32 vcc, 16, v28
	s_and_b64 exec, exec, vcc
	s_cbranch_execz .LBB0_1512
	v_lshl_add_u64 v[4:5], v[18:19], 0, v[20:21]
	s_waitcnt lgkmcnt(0)
	v_pk_add_f32 v[0:1], v[0:1], v[2:3]
	v_cmp_eq_u32_e32 vcc, 0, v28
	s_nop 1
	v_cndmask_b32_e32 v1, 0, v1, vcc
	v_cndmask_b32_e32 v0, 0, v0, vcc
	v_add_co_u32_e32 v2, vcc, 0x2f3e1000, v4
	s_nop 1
	v_addc_co_u32_e32 v3, vcc, 0, v5, vcc
	global_store_dwordx2 v[2:3], v[0:1], off

; #define GASP __attribute__((address_space(1)))
; template <int MODE> ...
;     const int lane = threadIdx.x & 63, gw = blockIdx.x * 8 + (threadIdx.x >> 6);
;     if (gw >= NS) return;
;     const int row = NP + gw;
;     f32x4 acc[4];
; #pragma unroll
;     for (int j = 0; j < 4; ++j) acc[j] = (f32x4){0.f, 0.f, 0.f, 0.f};
;     for (int ks = 0; ks < S; ++ks) { const GASP f32x4* sp = (const GASP f32x4*)(slab + ((size_t)ks * NS + gw) * D) + lane;
; #pragma unroll
;         for (int j = 0; j < 4; ++j) acc[j] = acc[j] + sp[64 * j]; }
;     float mu = 0.f, rstd = 1.f;
;     if (STp) { const GASP f32x4* sp = (const GASP f32x4*)(STp + (size_t)row * 32); float s = 0.f, q = 0.f;
; #pragma unroll
;         for (int i = 0; i < 8; ++i) { const f32x4 v = sp[i]; s += v[0] + v[2]; q += v[1] + v[3]; }
;         mu = s * (1.f / D); rstd = 1.f / sqrtf(q * (1.f / D) - mu * mu + LN_EPS); }
.LBB0_1718:
	s_cmp_lt_i32 s54, 17
	s_cselect_b64 s[0:1], -1, 0
	s_cmp_gt_i32 s55, 16
	s_cselect_b64 s[4:5], -1, 0
	s_and_b64 s[0:1], s[0:1], s[4:5]
	s_andn2_b64 vcc, exec, s[0:1]
	s_cbranch_vccnz .LBB0_1767
	s_waitcnt vmcnt(0)
	v_lshl_add_u32 v32, s2, 3, v209
	s_movk_i32 s0, 0x400
	v_cmp_gt_i32_e32 vcc, s0, v32
	s_and_saveexec_b64 s[12:13], vcc
	s_cbranch_execz .LBB0_1721
	v_ashrrev_i32_e32 v33, 31, v32
	v_and_b32_e32 v110, 63, v208
	s_waitcnt lgkmcnt(0)
	v_lshlrev_b64 v[0:1], 12, v[32:33]
	v_lshl_add_u64 v[0:1], s[52:53], 0, v[0:1]
	v_lshlrev_b32_e32 v108, 4, v110
	v_mov_b32_e32 v109, 0
	v_lshl_add_u64 v[104:105], v[0:1], 0, v[108:109]
	v_add_co_u32_e32 v0, vcc, 0x2fb47000, v104
	s_mov_b32 s0, 0x2ff47000
	s_nop 0
	v_addc_co_u32_e32 v1, vcc, 0, v105, vcc
	global_load_dwordx4 v[20:23], v[0:1], off
	v_add_co_u32_e32 v0, vcc, s0, v104
	s_mov_b32 s0, 0x30347000
	s_nop 0
	v_addc_co_u32_e32 v1, vcc, 0, v105, vcc
	global_load_dwordx4 v[44:47], v[0:1], off
	v_add_co_u32_e32 v0, vcc, s0, v104
	s_mov_b32 s0, 0x30747000
	s_nop 0
	v_addc_co_u32_e32 v1, vcc, 0, v105, vcc
	global_load_dwordx4 v[48:51], v[0:1], off
	v_add_co_u32_e32 v0, vcc, s0, v104
	s_mov_b32 s0, 0x30b47000
	s_nop 0
	v_addc_co_u32_e32 v1, vcc, 0, v105, vcc
	global_load_dwordx4 v[24:27], v[0:1], off
	v_add_co_u32_e32 v0, vcc, s0, v104
	v_readlane_b32 s0, v252, 1
	s_nop 0
	v_addc_co_u32_e32 v1, vcc, 0, v105, vcc
	global_load_dwordx4 v[28:31], v[0:1], off
	v_readlane_b32 s1, v252, 2
	s_load_dwordx4 s[8:11], s[0:1], 0xe0
	s_mov_b32 s0, 0x30f47000
	v_add_co_u32_e32 v0, vcc, s0, v104
	s_mov_b32 s1, 0x31347000
	s_nop 0
	v_addc_co_u32_e32 v1, vcc, 0, v105, vcc
	global_load_dwordx4 v[60:63], v[0:1], off
	v_add_co_u32_e32 v0, vcc, s1, v104
	s_mov_b32 s0, 0x31747000
	s_nop 0
	v_addc_co_u32_e32 v1, vcc, 0, v105, vcc
	global_load_dwordx4 v[64:67], v[0:1], off
	v_add_co_u32_e32 v0, vcc, s0, v104
	s_mov_b64 s[6:7], 0x2fb47000
	s_nop 0
	v_addc_co_u32_e32 v1, vcc, 0, v105, vcc
	global_load_dwordx4 v[68:71], v[0:1], off
	s_mov_b32 s3, 0x31b47000
	s_mov_b64 s[14:15], 0x2ff47000
	s_mov_b64 s[16:17], 0x30347000
	v_lshl_add_u64 v[34:35], v[104:105], 0, s[6:7]
	v_add_co_u32_e32 v56, vcc, s3, v104
	v_lshl_add_u64 v[52:53], v[104:105], 0, s[14:15]
	v_lshl_add_u64 v[54:55], v[104:105], 0, s[16:17]
	v_addc_co_u32_e32 v57, vcc, 0, v105, vcc
	global_load_dwordx4 v[36:39], v[34:35], off offset:1024
	global_load_dwordx4 v[12:15], v[34:35], off offset:2048
	global_load_dwordx4 v[40:43], v[52:53], off offset:1024
	global_load_dwordx4 v[16:19], v[52:53], off offset:2048
	global_load_dwordx4 v[0:3], v[52:53], off offset:3072
	global_load_dwordx4 v[92:95], v[56:57], off
	global_load_dwordx4 v[4:7], v[54:55], off offset:3072
	global_load_dwordx4 v[8:11], v[34:35], off offset:3072
	s_mov_b32 s4, 0x31f47000
	v_add_co_u32_e32 v58, vcc, s4, v104
	v_add_u32_e32 v76, 0x8000, v32
	s_nop 0
	v_addc_co_u32_e32 v59, vcc, 0, v105, vcc
	v_ashrrev_i32_e32 v77, 31, v76
	global_load_dwordx4 v[112:115], v[58:59], off
	s_mov_b64 s[0:1], 0x30747000
	s_mov_b32 s4, 0x3a800000
	s_mov_b32 s3, 0xf800000
	s_waitcnt vmcnt(16)
	v_pk_add_f32 v[20:21], v[20:21], 0 op_sel_hi:[1,0]
	v_pk_add_f32 v[22:23], v[22:23], 0 op_sel_hi:[1,0]
	s_waitcnt vmcnt(15)
	v_pk_add_f32 v[20:21], v[20:21], v[44:45]
	v_pk_add_f32 v[22:23], v[22:23], v[46:47]
	v_lshl_add_u64 v[46:47], v[104:105], 0, s[0:1]
	s_mov_b64 s[0:1], 0x30b47000
	s_waitcnt vmcnt(14)
	v_pk_add_f32 v[44:45], v[20:21], v[48:49]
	v_lshlrev_b64 v[20:21], 7, v[76:77]
	v_lshl_add_u64 v[32:33], s[46:47], 0, v[20:21]
	v_pk_add_f32 v[34:35], v[22:23], v[50:51]
	global_load_dwordx4 v[116:119], v[32:33], off offset:16
	global_load_dwordx4 v[120:123], v[32:33], off
	global_load_dwordx4 v[72:75], v[54:55], off offset:1024
	global_load_dwordx4 v[48:51], v[54:55], off offset:2048
	global_load_dwordx4 v[124:127], v[32:33], off offset:48
	global_load_dwordx4 v[128:131], v[32:33], off offset:32
	global_load_dwordx4 v[132:135], v[32:33], off offset:80
	global_load_dwordx4 v[136:139], v[32:33], off offset:64
	global_load_dwordx4 v[20:23], v[46:47], off offset:3072
	global_load_dwordx4 v[140:143], v[32:33], off offset:112
	global_load_dwordx4 v[144:147], v[32:33], off offset:96
	s_waitcnt vmcnt(24)
	v_pk_add_f32 v[32:33], v[44:45], v[24:25]
	v_lshl_add_u64 v[44:45], v[104:105], 0, s[0:1]
	s_mov_b32 s0, 0x32347000
	v_pk_add_f32 v[34:35], v[34:35], v[26:27]
	global_load_dwordx4 v[80:83], v[46:47], off offset:1024
	global_load_dwordx4 v[52:55], v[46:47], off offset:2048
	s_waitcnt vmcnt(25)
	v_pk_add_f32 v[32:33], v[32:33], v[28:29]
	v_add_co_u32_e32 v28, vcc, s0, v104
	global_load_dwordx4 v[24:27], v[44:45], off offset:3072
	s_nop 0
	v_addc_co_u32_e32 v29, vcc, 0, v105, vcc
	global_load_dwordx4 v[148:151], v[28:29], off
	global_load_dwordx4 v[84:87], v[44:45], off offset:1024
	global_load_dwordx4 v[56:59], v[44:45], off offset:2048
	s_mov_b64 s[0:1], 0x30f47000
	v_pk_add_f32 v[34:35], v[34:35], v[30:31]
	s_waitcnt vmcnt(28)
	v_pk_add_f32 v[78:79], v[32:33], v[60:61]
	v_lshl_add_u64 v[44:45], v[104:105], 0, s[0:1]
	s_mov_b64 s[0:1], 0x31347000
	v_lshlrev_b64 v[76:77], 11, v[76:77]
	global_load_dwordx4 v[28:31], v[44:45], off offset:3072
	v_pk_add_f32 v[46:47], v[34:35], v[62:63]
	s_waitcnt vmcnt(28)
	v_pk_add_f32 v[78:79], v[78:79], v[64:65]
	global_load_dwordx4 v[88:91], v[44:45], off offset:1024
	global_load_dwordx4 v[60:63], v[44:45], off offset:2048
	v_lshl_add_u64 v[44:45], v[104:105], 0, s[0:1]
	s_mov_b64 s[0:1], 0x31747000
	v_lshl_add_u64 v[76:77], s[42:43], 0, v[76:77]
	v_pk_add_f32 v[100:101], v[46:47], v[66:67]
	s_waitcnt vmcnt(29)
; #define GASP __attribute__((address_space(1)))
; template <int MODE> ...
;     ...
;     for (int ks = 0; ks < S; ++ks) { const GASP f32x4* sp = (const GASP f32x4*)(slab + ((size_t)ks * NS + gw) * D) + lane;
; #pragma unroll
;         for (int j = 0; j < 4; ++j) acc[j] = acc[j] + sp[64 * j]; }
;     float mu = 0.f, rstd = 1.f;
;     if (STp) { const GASP f32x4* sp = (const GASP f32x4*)(STp + (size_t)row * 32); float s = 0.f, q = 0.f;
; #pragma unroll
;         for (int i = 0; i < 8; ++i) { const f32x4 v = sp[i]; s += v[0] + v[2]; q += v[1] + v[3]; }
;         mu = s * (1.f / D); rstd = 1.f / sqrtf(q * (1.f / D) - mu * mu + LN_EPS); }
;     if (MODE == 0) {
;         const GASP f32x4* rp = (const GASP f32x4*)(res + (size_t)row * D) + lane;
;         float s = 0.f, q = 0.f;
; #pragma unroll
;         for (int j = 0; j < 4; ++j) { f32x4 r;
;             if (resb) { const u32x2 w = ((const GASP u32x2*)(resb + (size_t)row * D))[64 * j + lane];
;                 r = (f32x4){__uint_as_float(w.x << 16), __uint_as_float(w.x & 0xffff0000u), __uint_as_float(w.y << 16), __uint_as_float(w.y & 0xffff0000u)}; }
;             else r = rp[64 * j];
;             if (STp) r = (r - mu) * rstd * ((const GASP f32x4*)gam)[64 * j + lane] + ((const GASP f32x4*)bet)[64 * j + lane];
	v_pk_add_f32 v[154:155], v[78:79], v[68:69]
	v_lshlrev_b32_e32 v78, 3, v110
	v_mov_b32_e32 v79, v109
	v_lshl_add_u64 v[106:107], v[104:105], 0, s[0:1]
	v_lshl_add_u64 v[110:111], v[76:77], 0, v[78:79]
	global_load_dwordx4 v[32:35], v[44:45], off offset:3072
	global_load_dwordx4 v[96:99], v[44:45], off offset:1024
	global_load_dwordx4 v[64:67], v[44:45], off offset:2048
	v_pk_add_f32 v[152:153], v[100:101], v[70:71]
	global_load_dwordx4 v[44:47], v[106:107], off offset:3072
	global_load_dwordx4 v[100:103], v[106:107], off offset:1024
	global_load_dwordx4 v[68:71], v[106:107], off offset:2048
	global_load_dwordx2 v[176:177], v[110:111], off
	s_mov_b64 s[0:1], 0x31b47000
	v_lshl_add_u64 v[106:107], v[104:105], 0, s[0:1]
	global_load_dwordx4 v[76:79], v[106:107], off offset:3072
	s_waitcnt vmcnt(31)
	v_pk_add_f32 v[168:169], v[152:153], v[94:95]
	v_pk_add_f32 v[170:171], v[154:155], v[92:93]
	global_load_dwordx4 v[152:155], v[106:107], off offset:1024
	global_load_dwordx4 v[156:159], v[106:107], off offset:2048
	s_waitcnt lgkmcnt(0)
	global_load_dwordx4 v[160:163], v108, s[8:9]
	global_load_dwordx4 v[164:167], v108, s[10:11]
	s_mov_b64 s[0:1], 0x31f47000
	v_lshl_add_u64 v[106:107], v[104:105], 0, s[0:1]
	global_load_dwordx4 v[92:95], v[106:107], off offset:3072
	s_waitcnt vmcnt(33)
	v_pk_add_f32 v[114:115], v[168:169], v[114:115]
	v_pk_add_f32 v[178:179], v[170:171], v[112:113]
	global_load_dwordx4 v[168:171], v[106:107], off offset:1024
	global_load_dwordx4 v[172:175], v[106:107], off offset:2048
	s_mov_b64 s[0:1], 0x32347000
	v_pk_add_f32 v[38:39], v[38:39], 0 op_sel_hi:[1,0]
	v_pk_add_f32 v[36:37], v[36:37], 0 op_sel_hi:[1,0]
	v_pk_add_f32 v[38:39], v[38:39], v[42:43]
	v_pk_add_f32 v[36:37], v[36:37], v[40:41]
	v_pk_add_f32 v[14:15], v[14:15], 0 op_sel_hi:[1,0]
	v_pk_add_f32 v[12:13], v[12:13], 0 op_sel_hi:[1,0]
	v_pk_add_f32 v[14:15], v[14:15], v[18:19]
	v_pk_add_f32 v[12:13], v[12:13], v[16:17]
	v_pk_add_f32 v[10:11], v[10:11], 0 op_sel_hi:[1,0]
	v_pk_add_f32 v[8:9], v[8:9], 0 op_sel_hi:[1,0]
	v_pk_add_f32 v[2:3], v[10:11], v[2:3]
	v_pk_add_f32 v[0:1], v[8:9], v[0:1]
	v_pk_add_f32 v[2:3], v[2:3], v[6:7]
	v_pk_add_f32 v[0:1], v[0:1], v[4:5]
	s_waitcnt vmcnt(34)
	v_pk_add_f32 v[112:113], v[116:117], v[118:119]
	s_waitcnt vmcnt(33)
	v_pk_add_f32 v[106:107], v[120:121], v[122:123]
	v_lshl_add_u64 v[118:119], v[104:105], 0, s[0:1]
	v_pk_add_f32 v[106:107], v[106:107], 0 op_sel_hi:[1,0]
	s_waitcnt vmcnt(32)
	v_pk_add_f32 v[38:39], v[38:39], v[74:75]
	v_pk_add_f32 v[106:107], v[106:107], v[112:113]
	s_waitcnt vmcnt(29)
	v_pk_add_f32 v[112:113], v[128:129], v[130:131]
	v_pk_add_f32 v[36:37], v[36:37], v[72:73]
	v_pk_add_f32 v[106:107], v[106:107], v[112:113]
	v_pk_add_f32 v[112:113], v[124:125], v[126:127]
	v_pk_add_f32 v[14:15], v[14:15], v[50:51]
	v_pk_add_f32 v[106:107], v[106:107], v[112:113]
	s_waitcnt vmcnt(27)
	v_pk_add_f32 v[112:113], v[136:137], v[138:139]
	s_waitcnt vmcnt(23)
	v_pk_add_f32 v[38:39], v[38:39], v[82:83]
	v_pk_add_f32 v[106:107], v[106:107], v[112:113]
	v_pk_add_f32 v[112:113], v[132:133], v[134:135]
	v_pk_add_f32 v[36:37], v[36:37], v[80:81]
	v_pk_add_f32 v[106:107], v[106:107], v[112:113]
	v_pk_add_f32 v[112:113], v[144:145], v[146:147]
	s_waitcnt vmcnt(20)
	v_pk_add_f32 v[122:123], v[114:115], v[150:151]
	v_pk_add_f32 v[106:107], v[106:107], v[112:113]
	v_pk_add_f32 v[112:113], v[140:141], v[142:143]
	v_pk_add_f32 v[124:125], v[178:179], v[148:149]
	v_pk_add_f32 v[106:107], v[106:107], v[112:113]
	s_waitcnt vmcnt(19)
	v_pk_add_f32 v[38:39], v[38:39], v[86:87]
	v_pk_mul_f32 v[112:113], v[106:107], s[4:5] op_sel_hi:[1,0]
	v_pk_add_f32 v[36:37], v[36:37], v[84:85]
	v_fma_f32 v106, -v112, v112, v113
	v_add_f32_e32 v106, 0x3727c5ac, v106
	v_mul_f32_e32 v107, 0x4f800000, v106
	v_cmp_gt_f32_e32 vcc, s3, v106
	s_waitcnt vmcnt(16)
	v_pk_add_f32 v[38:39], v[38:39], v[90:91]
	v_pk_add_f32 v[36:37], v[36:37], v[88:89]
	v_cndmask_b32_e32 v109, v106, v107, vcc
	v_sqrt_f32_e32 v113, v109
	global_load_dwordx4 v[104:107], v[118:119], off offset:3072
	v_pk_add_f32 v[12:13], v[12:13], v[48:49]
	v_pk_add_f32 v[14:15], v[14:15], v[54:55]
	v_add_u32_e32 v114, -1, v113
	v_fma_f32 v115, -v114, v113, v109
	v_cmp_ge_f32_e64 s[6:7], 0, v115
	v_add_u32_e32 v115, 1, v113
	s_waitcnt vmcnt(14)
	v_pk_add_f32 v[38:39], v[38:39], v[98:99]
	v_cndmask_b32_e64 v114, v113, v114, s[6:7]
	v_fma_f32 v113, -v115, v113, v109
	v_cmp_lt_f32_e64 s[6:7], 0, v113
	v_pk_add_f32 v[36:37], v[36:37], v[96:97]
	s_waitcnt vmcnt(11)
	v_pk_add_f32 v[38:39], v[38:39], v[102:103]
	v_cndmask_b32_e64 v113, v114, v115, s[6:7]
	v_mul_f32_e32 v114, 0x37800000, v113
	v_cndmask_b32_e32 v113, v113, v114, vcc
	v_mov_b32_e32 v114, 0x260
	v_cmp_class_f32_e32 vcc, v109, v114
	s_mov_b32 s6, 0x3f9837f0
	global_load_dwordx4 v[114:117], v[118:119], off offset:1024
	s_nop 0
	global_load_dwordx4 v[118:121], v[118:119], off offset:2048
	v_cndmask_b32_e32 v109, v113, v109, vcc
	v_div_scale_f32 v113, s[0:1], v109, v109, 1.0
	v_rcp_f32_e32 v126, v113
	global_load_dwordx2 v[132:133], v[110:111], off offset:512
	global_load_dwordx2 v[134:135], v[110:111], off offset:1024
	global_load_dwordx2 v[136:137], v[110:111], off offset:1536
	v_pk_add_f32 v[36:37], v[36:37], v[100:101]
	s_waitcnt vmcnt(12)
; #define GASP __attribute__((address_space(1)))
; template <int MODE> ...
;     ...
;         for (int j = 0; j < 4; ++j) { f32x4 r;
;             if (resb) { const u32x2 w = ((const GASP u32x2*)(resb + (size_t)row * D))[64 * j + lane];
;                 r = (f32x4){__uint_as_float(w.x << 16), __uint_as_float(w.x & 0xffff0000u), __uint_as_float(w.y << 16), __uint_as_float(w.y & 0xffff0000u)}; }
;             else r = rp[64 * j];
;             if (STp) r = (r - mu) * rstd * ((const GASP f32x4*)gam)[64 * j + lane] + ((const GASP f32x4*)bet)[64 * j + lane];
;             const f32x4 o = r * ALPHA + acc[j] * scale;
;             if (out) ((GASP f32x4*)(out + (size_t)row * D))[64 * j + lane] = o;
;             if (ob) { u32x2 w; w.x = pk2(o[0], o[1]); w.y = pk2(o[2], o[3]); ((GASP u32x2*)(ob + (size_t)row * D))[64 * j + lane] = w; }
	v_pk_add_f32 v[38:39], v[38:39], v[154:155]
	v_fma_f32 v127, -v113, v126, 1.0
	v_fmac_f32_e32 v126, v127, v126
	v_div_scale_f32 v127, vcc, 1.0, v109, 1.0
	v_mul_f32_e32 v128, v127, v126
	v_fma_f32 v129, -v113, v128, v127
	v_fmac_f32_e32 v128, v129, v126
	v_fma_f32 v113, -v113, v128, v127
	v_div_fmas_f32 v113, v113, v126, v128
	v_div_fixup_f32 v130, v113, v109, 1.0
	v_lshlrev_b32_e32 v109, 16, v176
	v_and_b32_e32 v113, 0xffff0000, v176
	v_lshlrev_b32_e32 v126, 16, v177
	v_and_b32_e32 v127, 0xffff0000, v177
	v_sub_f32_e32 v127, v127, v112
	v_sub_f32_e32 v126, v126, v112
	v_sub_f32_e32 v129, v113, v112
	v_sub_f32_e32 v128, v109, v112
	v_pk_mul_f32 v[128:129], v[128:129], v[130:131] op_sel_hi:[1,0]
	v_pk_mul_f32 v[126:127], v[126:127], v[130:131] op_sel_hi:[1,0]
	s_waitcnt vmcnt(9)
	v_pk_fma_f32 v[128:129], v[160:161], v[128:129], v[164:165]
	v_pk_fma_f32 v[126:127], v[162:163], v[126:127], v[166:167]
	v_pk_mul_f32 v[128:129], v[128:129], s[6:7] op_sel_hi:[1,0]
	v_pk_mul_f32 v[126:127], v[126:127], s[6:7] op_sel_hi:[1,0]
	v_pk_fma_f32 v[124:125], v[124:125], 0.5, v[128:129] op_sel_hi:[1,0,1]
	v_pk_fma_f32 v[122:123], v[122:123], 0.5, v[126:127] op_sel_hi:[1,0,1]
	v_cvt_pk_bf16_f32 v124, v124, v125
	v_cvt_pk_bf16_f32 v125, v122, v123
	global_store_dwordx2 v[110:111], v[124:125], off
	global_load_dwordx4 v[122:125], v108, s[8:9] offset:1024
	s_nop 0
	global_load_dwordx4 v[126:129], v108, s[10:11] offset:1024
	global_load_dwordx4 v[180:183], v108, s[8:9] offset:2048
	global_load_dwordx4 v[184:187], v108, s[10:11] offset:2048
	global_load_dwordx4 v[188:191], v108, s[8:9] offset:3072
	global_load_dwordx4 v[192:195], v108, s[10:11] offset:3072
	v_pk_add_f32 v[36:37], v[36:37], v[152:153]
	s_waitcnt vmcnt(14)
	v_pk_add_f32 v[38:39], v[38:39], v[170:171]
	v_pk_add_f32 v[36:37], v[36:37], v[168:169]
	v_pk_add_f32 v[12:13], v[12:13], v[52:53]
	v_pk_add_f32 v[14:15], v[14:15], v[58:59]
	v_pk_add_f32 v[12:13], v[12:13], v[56:57]
	v_pk_add_f32 v[14:15], v[14:15], v[62:63]
	v_pk_add_f32 v[12:13], v[12:13], v[60:61]
	v_pk_add_f32 v[14:15], v[14:15], v[66:67]
	v_pk_add_f32 v[12:13], v[12:13], v[64:65]
	v_pk_add_f32 v[14:15], v[14:15], v[70:71]
	v_pk_add_f32 v[12:13], v[12:13], v[68:69]
	v_pk_add_f32 v[14:15], v[14:15], v[158:159]
	v_pk_add_f32 v[12:13], v[12:13], v[156:157]
	s_waitcnt vmcnt(13)
	v_pk_add_f32 v[14:15], v[14:15], v[174:175]
	v_pk_add_f32 v[12:13], v[12:13], v[172:173]
	v_pk_add_f32 v[2:3], v[2:3], v[22:23]
	v_pk_add_f32 v[0:1], v[0:1], v[20:21]
	v_pk_add_f32 v[2:3], v[2:3], v[26:27]
	v_pk_add_f32 v[0:1], v[0:1], v[24:25]
	v_pk_add_f32 v[2:3], v[2:3], v[30:31]
	v_pk_add_f32 v[0:1], v[0:1], v[28:29]
	v_pk_add_f32 v[2:3], v[2:3], v[34:35]
	v_pk_add_f32 v[0:1], v[0:1], v[32:33]
	v_pk_add_f32 v[2:3], v[2:3], v[46:47]
	v_pk_add_f32 v[0:1], v[0:1], v[44:45]
	v_pk_add_f32 v[2:3], v[2:3], v[78:79]
	v_pk_add_f32 v[0:1], v[0:1], v[76:77]
	v_pk_add_f32 v[2:3], v[2:3], v[94:95]
	v_pk_add_f32 v[0:1], v[0:1], v[92:93]
	s_waitcnt vmcnt(12)
	v_pk_add_f32 v[2:3], v[2:3], v[106:107]
	v_pk_add_f32 v[0:1], v[0:1], v[104:105]
	s_waitcnt vmcnt(11)
	v_pk_add_f32 v[38:39], v[38:39], v[116:117]
	v_pk_add_f32 v[36:37], v[36:37], v[114:115]
	s_waitcnt vmcnt(10)
	v_pk_add_f32 v[14:15], v[14:15], v[120:121]
	v_pk_add_f32 v[12:13], v[12:13], v[118:119]
	s_waitcnt vmcnt(9)
	v_lshlrev_b32_e32 v42, 16, v132
	v_and_b32_e32 v43, 0xffff0000, v132
	v_lshlrev_b32_e32 v40, 16, v133
	v_and_b32_e32 v41, 0xffff0000, v133
	v_sub_f32_e32 v41, v41, v112
	v_sub_f32_e32 v40, v40, v112
	v_sub_f32_e32 v43, v43, v112
	v_sub_f32_e32 v42, v42, v112
	v_pk_mul_f32 v[42:43], v[130:131], v[42:43] op_sel_hi:[0,1]
	v_pk_mul_f32 v[40:41], v[130:131], v[40:41] op_sel_hi:[0,1]
	s_waitcnt vmcnt(8)
	v_lshlrev_b32_e32 v18, 16, v134
	v_and_b32_e32 v19, 0xffff0000, v134
	v_lshlrev_b32_e32 v16, 16, v135
	v_and_b32_e32 v17, 0xffff0000, v135
	v_sub_f32_e32 v17, v17, v112
	v_sub_f32_e32 v16, v16, v112
	v_sub_f32_e32 v19, v19, v112
	v_sub_f32_e32 v18, v18, v112
	v_pk_mul_f32 v[18:19], v[130:131], v[18:19] op_sel_hi:[0,1]
	v_pk_mul_f32 v[16:17], v[130:131], v[16:17] op_sel_hi:[0,1]
	s_waitcnt vmcnt(0)
	v_pk_fma_f32 v[40:41], v[124:125], v[40:41], v[128:129]
	v_pk_fma_f32 v[42:43], v[122:123], v[42:43], v[126:127]
	v_pk_mul_f32 v[40:41], v[40:41], s[6:7] op_sel_hi:[1,0]
	v_pk_mul_f32 v[42:43], v[42:43], s[6:7] op_sel_hi:[1,0]
	v_pk_fma_f32 v[38:39], v[38:39], 0.5, v[40:41] op_sel_hi:[1,0,1]
	v_pk_fma_f32 v[36:37], v[36:37], 0.5, v[42:43] op_sel_hi:[1,0,1]
	s_nop 0
	v_cvt_pk_bf16_f32 v36, v36, v37
	v_cvt_pk_bf16_f32 v37, v38, v39
	global_store_dwordx2 v[110:111], v[36:37], off offset:512
	s_nop 0
	v_pk_fma_f32 v[16:17], v[182:183], v[16:17], v[186:187]
	v_pk_fma_f32 v[18:19], v[180:181], v[18:19], v[184:185]
	v_pk_mul_f32 v[16:17], v[16:17], s[6:7] op_sel_hi:[1,0]
	v_pk_mul_f32 v[18:19], v[18:19], s[6:7] op_sel_hi:[1,0]
	v_pk_fma_f32 v[14:15], v[14:15], 0.5, v[16:17] op_sel_hi:[1,0,1]
	v_pk_fma_f32 v[12:13], v[12:13], 0.5, v[18:19] op_sel_hi:[1,0,1]
	v_lshlrev_b32_e32 v36, 16, v136
	v_cvt_pk_bf16_f32 v12, v12, v13
	v_cvt_pk_bf16_f32 v13, v14, v15
	global_store_dwordx2 v[110:111], v[12:13], off offset:1024
	s_nop 0
	v_and_b32_e32 v37, 0xffff0000, v136
	v_lshlrev_b32_e32 v38, 16, v137
	v_and_b32_e32 v39, 0xffff0000, v137
	v_sub_f32_e32 v5, v39, v112
	v_sub_f32_e32 v4, v38, v112
	v_sub_f32_e32 v7, v37, v112
	v_sub_f32_e32 v6, v36, v112
	v_pk_mul_f32 v[6:7], v[130:131], v[6:7] op_sel_hi:[0,1]
	v_pk_mul_f32 v[4:5], v[130:131], v[4:5] op_sel_hi:[0,1]
	v_pk_fma_f32 v[4:5], v[190:191], v[4:5], v[194:195]
	v_pk_fma_f32 v[6:7], v[188:189], v[6:7], v[192:193]
	v_pk_mul_f32 v[4:5], v[4:5], s[6:7] op_sel_hi:[1,0]
	v_pk_mul_f32 v[6:7], v[6:7], s[6:7] op_sel_hi:[1,0]
	v_pk_fma_f32 v[2:3], v[2:3], 0.5, v[4:5] op_sel_hi:[1,0,1]
	v_pk_fma_f32 v[0:1], v[0:1], 0.5, v[6:7] op_sel_hi:[1,0,1]
	s_nop 0
	v_cvt_pk_bf16_f32 v0, v0, v1
	v_cvt_pk_bf16_f32 v1, v2, v3
	global_store_dwordx2 v[110:111], v[0:1], off offset:1536
